# DF late-half step: d-block 2,3 fragment reads issued as each d-block 0,1 MFMA frees its quad (was all 16 after the 8th MFMA)
# speedup vs baseline: 1.0025x; 1.0008x over previous
.LBB0_408:
	s_andn2_b64 vcc, exec, s[10:11]
	s_cbranch_vccnz .LBB0_410
	s_lshl_b32 s10, s24, 14
	s_addk_i32 s10, 0xc000
	s_cmp_gt_i32 s24, 0
	s_cselect_b32 s10, s10, 0x10000
	v_add_u32_e32 v203, s10, v221
	s_nop 4
	ds_read_b64_tr_b16 v[80:81], v203
	ds_read_b64_tr_b16 v[82:83], v203 offset:512
	ds_read_b64_tr_b16 v[84:85], v203 offset:1024
	ds_read_b64_tr_b16 v[86:87], v203 offset:1536
	ds_read_b64_tr_b16 v[88:89], v203 offset:4096
	ds_read_b64_tr_b16 v[90:91], v203 offset:4608
	ds_read_b64_tr_b16 v[92:93], v203 offset:5120
	ds_read_b64_tr_b16 v[94:95], v203 offset:5632
	ds_read_b64_tr_b16 v[96:97], v203 offset:2048
	ds_read_b64_tr_b16 v[98:99], v203 offset:2560
	ds_read_b64_tr_b16 v[100:101], v203 offset:3072
	ds_read_b64_tr_b16 v[102:103], v203 offset:3584
	ds_read_b64_tr_b16 v[104:105], v203 offset:6144
	ds_read_b64_tr_b16 v[106:107], v203 offset:6656
	ds_read_b64_tr_b16 v[108:109], v203 offset:7168
	ds_read_b64_tr_b16 v[110:111], v203 offset:7680
	ds_read_b128 v[204:207], v202
	ds_read_b128 v[208:211], v202 offset:4096
	ds_read_b128 v[212:215], v15
	ds_read_b128 v[238:241], v15 offset:4096
	ds_read_b128 v[242:245], v14
	v_mov_b32_e32 v202, v246
	ds_read_b128 v[246:249], v14 offset:4096
	ds_read_b128 v[250:253], v0
	ds_read_b128 v[148:151], v0 offset:4096
	s_waitcnt lgkmcnt(14)
	v_mfma_f32_32x32x16_bf16 v[64:79], v[80:83], v[144:147], v[64:79]
	ds_read_b64_tr_b16 v[80:81], v203 offset:8192
	ds_read_b64_tr_b16 v[82:83], v203 offset:8704
	v_mfma_f32_32x32x16_bf16 v[48:63], v[88:91], v[144:147], v[48:63]
	ds_read_b64_tr_b16 v[88:89], v203 offset:12288
	ds_read_b64_tr_b16 v[90:91], v203 offset:12800
	v_mfma_f32_32x32x16_bf16 v[64:79], v[84:87], v[10:13], v[64:79]
	ds_read_b64_tr_b16 v[84:85], v203 offset:9216
	ds_read_b64_tr_b16 v[86:87], v203 offset:9728
	v_mfma_f32_32x32x16_bf16 v[48:63], v[92:95], v[10:13], v[48:63]
	ds_read_b64_tr_b16 v[92:93], v203 offset:13312
	ds_read_b64_tr_b16 v[94:95], v203 offset:13824
	v_mfma_f32_32x32x16_bf16 v[64:79], v[96:99], v[6:9], v[64:79]
	ds_read_b64_tr_b16 v[96:97], v203 offset:10240
	ds_read_b64_tr_b16 v[98:99], v203 offset:10752
	s_waitcnt lgkmcnt(10)
	v_mfma_f32_32x32x16_bf16 v[48:63], v[104:107], v[6:9], v[48:63]
	ds_read_b64_tr_b16 v[104:105], v203 offset:14336
	ds_read_b64_tr_b16 v[106:107], v203 offset:14848
	v_mfma_f32_32x32x16_bf16 v[64:79], v[100:103], v[2:5], v[64:79]
	ds_read_b64_tr_b16 v[100:101], v203 offset:11264
	ds_read_b64_tr_b16 v[102:103], v203 offset:11776
	v_mfma_f32_32x32x16_bf16 v[48:63], v[108:111], v[2:5], v[48:63]
	ds_read_b64_tr_b16 v[108:109], v203 offset:15360
	ds_read_b64_tr_b16 v[110:111], v203 offset:15872
	s_waitcnt lgkmcnt(14)
	v_mfma_f32_32x32x16_bf16 v[32:47], v[80:83], v[144:147], v[32:47]
	s_waitcnt lgkmcnt(12)
	v_mfma_f32_32x32x16_bf16 v[16:31], v[88:91], v[144:147], v[16:31]
	s_waitcnt lgkmcnt(10)
	v_mfma_f32_32x32x16_bf16 v[32:47], v[84:87], v[10:13], v[32:47]
	s_waitcnt lgkmcnt(8)
	v_mfma_f32_32x32x16_bf16 v[16:31], v[92:95], v[10:13], v[16:31]
	s_waitcnt lgkmcnt(6)
	v_mfma_f32_32x32x16_bf16 v[32:47], v[96:99], v[6:9], v[32:47]
	s_waitcnt lgkmcnt(4)
	v_mfma_f32_32x32x16_bf16 v[16:31], v[104:107], v[6:9], v[16:31]
	s_waitcnt lgkmcnt(2)
	v_mfma_f32_32x32x16_bf16 v[32:47], v[100:103], v[2:5], v[32:47]
	s_waitcnt lgkmcnt(0)
	v_mfma_f32_32x32x16_bf16 v[16:31], v[108:111], v[2:5], v[16:31]
	v_mfma_f32_32x32x16_bf16 v[96:111], v[204:207], v[136:139], 0
	v_mfma_f32_32x32x16_bf16 v[80:95], v[208:211], v[136:139], 0
	v_mfma_f32_32x32x16_bf16 v[96:111], v[212:215], v[128:131], v[96:111]
	v_mfma_f32_32x32x16_bf16 v[80:95], v[238:241], v[128:131], v[80:95]
	v_mfma_f32_32x32x16_bf16 v[96:111], v[242:245], v[140:143], v[96:111]
	v_mfma_f32_32x32x16_bf16 v[80:95], v[246:249], v[140:143], v[80:95]
	v_mov_b32_e32 v246, v202
	v_mfma_f32_32x32x16_bf16 v[96:111], v[250:253], v[132:135], v[96:111]
	v_mfma_f32_32x32x16_bf16 v[80:95], v[148:151], v[132:135], v[80:95]
